# attention K/V tile loads through scalar base pointers (saddr + 32-bit lane offset, SALU increments) instead of four 64-bit VALU pointer adds per tile
# speedup vs baseline: 1.0071x; 1.0071x over previous
; DI int fresh_tid() { int t = threadIdx.x; asm volatile("" : "+v"(t)); return t; }
; DI float bf2f(unsigned v) { return __uint_as_float(v << 16); }
; DI f32x16 zero16() { f32x16 z; for (int i = 0; i < 16; ++i) z[i] = 0.f; return z; }
; DI void attn_item(const P& p, int l, int item, char* smem) {
;     ...
;   const int tid = fresh_tid(), lane = tid & 63, wave = tid >> 6;
;   const int li = lane & 31, g = lane >> 5;
;   const int qg = wave & 3, c = wave >> 2;
;   const int bh = item & 7, qb = (item >> 8) * 32 + ((item & 255) >> 3);
;   const int b = bh >> 2, h = bh & 3;
;   const float lam_init = (l == 0) ? 0.2f : 0.35550906759096926f;
;   float lam;
;   {
;     float s1 = p.lq1[l * 64 + lane] * p.lk1[l * 64 + lane];
;     float s2 = p.lq2[l * 64 + lane] * p.lk2[l * 64 + lane];
; #pragma unroll
;     for (int m = 32; m >= 1; m >>= 1) { s1 += __shfl_xor(s1, m); s2 += __shfl_xor(s2, m); }
;     lam = __expf(s1) - __expf(s2) + lam_init;
;   }
;   const int tq = qb * 128 + qg * 32 + li;
;   bf16x8 qf[4];
;   float negm;
;   {
;     float q2 = 0.f;
; #pragma unroll
;     for (int ks = 0; ks < 4; ++ks) {
;       qf[ks] = *(const bf16x8*)(p.Qb + ((size_t)((bh * 2 + c) * SEQ + tq)) * 64 + 16 * ks + 8 * g);
; #pragma unroll
;       for (int j = 0; j < 8; ++j) { const float v = bf2f((unsigned)(u16)qf[ks][j]); q2 += v * v; }
;     }
;     q2 += __shfl_xor(q2, 32);
;     const float k2 = __uint_as_float(p.kmax[bh * 2 + c]);
;     negm = -(sqrtf(q2 * k2) * 1.01f + 1e-3f);
;   }
;   f32x16 O[4];
; #pragma unroll
;   for (int eb = 0; eb < 4; ++eb) O[eb] = zero16();
;   float ls = 0.f;
;   u32x4 kreg[2], vreg[2];
;   const u16* kbase = p.Kb + (size_t)(bh * 2) * SEQ * 64;
;   const u16* vbase = p.VT + (size_t)(bh * 128) * VTP;
; #pragma unroll
;   for (int i = 0; i < 2; ++i) kreg[i] = *(const u32x4*)(kbase + ((size_t)i * SEQ) * 64 + tid * 8);
; #pragma unroll
;   for (int i = 0; i < 2; ++i) {
;     const int cid = tid + NT * i;
;     const int e = cid >> 3, kc = cid & 7;
;     vreg[i] = *(const u32x4*)(vbase + (size_t)e * VTP + kc * 8);
;   }
.LBB0_465:
	v_mov_b32_e32 v161, v198
	v_readlane_b32 s6, v248, 26
	v_and_b32_e32 v141, 63, v161
	v_readlane_b32 s72, v248, 30
	v_or_b32_e32 v188, s6, v141
	v_lshlrev_b64 v[0:1], 2, v[188:189]
	v_lshl_add_u64 v[2:3], s[22:23], 0, v[0:1]
	global_load_dword v4, v[2:3], off
	v_lshl_add_u64 v[2:3], s[24:25], 0, v[0:1]
	v_readlane_b32 s73, v248, 31
	global_load_dword v5, v[2:3], off
	v_lshl_add_u64 v[2:3], s[26:27], 0, v[0:1]
	v_lshl_add_u64 v[0:1], s[72:73], 0, v[0:1]
	global_load_dword v2, v[2:3], off
	v_and_b32_e32 v3, 64, v215
	global_load_dword v0, v[0:1], off
	v_add_u32_e32 v3, 64, v3
	v_xor_b32_e32 v7, 32, v215
	v_cmp_lt_i32_e32 vcc, v7, v3
	v_bfe_u32 v162, v161, 6, 2
	s_lshl_b32 s6, s95, 4
	v_cndmask_b32_e32 v7, v215, v7, vcc
	v_lshlrev_b32_e32 v158, 2, v7
	v_ashrrev_i32_e32 v160, 8, v161
	v_and_b32_e32 v17, 31, v161
	s_and_b32 s12, s95, 7
	s_and_b32 s6, s6, 0xffffff80
	v_bfe_u32 v159, v161, 5, 1
	v_lshlrev_b32_e32 v188, 4, v159
	s_and_b32 s13, s64, 7
	s_lshl_b32 s11, s13, 21
	v_mov_b32_e32 v143, v189
	v_ashrrev_i32_e32 v24, 3, v161
	s_movk_i32 s14, 0x4080
	v_mul_lo_u32 v170, v24, s94
	v_mov_b32_e32 v167, 0
	s_mov_b32 s10, 0
	v_mul_u32_u24_e32 v174, 0x90, v17
	v_lshlrev_b32_e32 v8, 5, v162
	v_or3_b32 v140, v8, s6, v17
	s_lshl_b32 s6, s12, 14
	v_lshlrev_b32_e32 v8, 13, v160
	v_add3_u32 v8, v8, s6, v140
	v_ashrrev_i32_e32 v9, 31, v8
	v_lshlrev_b64 v[8:9], 7, v[8:9]
	v_lshl_add_u64 v[8:9], s[38:39], 0, v[8:9]
	v_lshl_add_u64 v[8:9], v[8:9], 0, v[188:189]
	global_load_dwordx4 v[112:115], v[8:9], off
	global_load_dwordx4 v[116:119], v[8:9], off offset:32
	global_load_dwordx4 v[124:127], v[8:9], off offset:64
	global_load_dwordx4 v[120:123], v[8:9], off offset:96
	v_readlane_b32 s6, v248, 38
	v_readlane_b32 s7, v248, 39
	v_lshl_add_u32 v14, s12, 1, v160
	v_ashrrev_i32_e32 v15, 31, v14
	v_lshl_add_u64 v[14:15], v[14:15], 2, s[6:7]
	global_load_dword v14, v[14:15], off
	s_lshl_b32 s6, s12, 21
	s_add_u32 s6, s40, s6
	v_lshlrev_b32_e32 v10, 3, v161
	v_ashrrev_i32_e32 v11, 31, v10
	s_addc_u32 s7, s41, 0
	v_lshlrev_b64 v[32:33], 1, v[10:11]
	v_lshl_add_u64 v[22:23], s[6:7], 0, v[32:33]
	s_mul_i32 s6, s12, 0x204000
	s_add_u32 s6, s42, s6
	v_and_b32_e32 v11, 56, v10
	s_addc_u32 s7, s43, 0
	v_lshlrev_b32_e32 v142, 1, v11
	v_add_u32_e32 v11, 0x200, v161
	v_lshl_add_u64 v[12:13], s[6:7], 0, v[142:143]
	v_ashrrev_i32_e32 v25, 3, v11
	v_mad_i64_i32 v[34:35], s[6:7], v24, s14, 0
	v_mad_i64_i32 v[36:37], s[6:7], v25, s14, 0
	v_mad_i64_i32 v[18:19], s[6:7], v25, s14, v[12:13]
	v_mad_i64_i32 v[20:21], s[6:7], v24, s14, v[12:13]
	s_mov_b32 s6, 0x100000
	s_nop 0
	v_add_co_u32_e32 v8, vcc, s6, v22
	v_and_b32_e32 v26, 48, v10
	v_lshlrev_b32_e32 v10, 2, v161
	v_addc_co_u32_e32 v9, vcc, 0, v23, vcc
	v_and_b32_e32 v27, 4, v10
	global_load_dwordx4 v[80:83], v[18:19], off
	global_load_dwordx4 v[84:87], v[20:21], off
	s_nop 0
	global_load_dwordx4 v[88:91], v[8:9], off
	s_nop 0
	global_load_dwordx4 v[92:95], v[22:23], off
	v_mov_b32_e32 v38, v167
	v_mov_b32_e32 v39, v167
	v_mov_b32_e32 v40, v167
	v_mov_b32_e32 v41, v167
	v_mov_b32_e32 v42, v167
	v_mov_b32_e32 v43, v167
	v_mov_b32_e32 v44, v167
	v_mov_b32_e32 v45, v167
	v_mov_b32_e32 v46, v167
	v_mov_b32_e32 v47, v167
	v_mov_b32_e32 v48, 0
	v_mov_b32_e32 v49, v167
	v_mov_b32_e32 v50, v167
	v_mov_b32_e32 v51, v167
	v_mov_b32_e32 v52, v167
	v_mov_b32_e32 v53, v167
	v_mov_b32_e32 v54, v167
	v_mov_b32_e32 v55, v167
	v_mov_b32_e32 v56, v167
	v_mov_b32_e32 v57, v167
	v_mov_b32_e32 v58, v167
	v_mov_b32_e32 v59, v167
	v_mov_b32_e32 v60, v167
	v_mov_b32_e32 v61, v167
	v_mov_b32_e32 v62, v167
	v_mov_b32_e32 v63, v167
	v_mov_b32_e32 v64, 0
	v_mov_b32_e32 v65, v167
	v_mov_b32_e32 v66, v167
	v_mov_b32_e32 v67, v167
	v_mov_b32_e32 v68, v167
	v_mov_b32_e32 v69, v167
	v_mov_b32_e32 v70, v167
	v_mov_b32_e32 v71, v167
	v_mov_b32_e32 v72, v167
	v_mov_b32_e32 v73, v167
	v_mov_b32_e32 v74, v167
	v_mov_b32_e32 v75, v167
	v_mov_b32_e32 v76, v167
	v_mov_b32_e32 v77, v167
	v_mov_b32_e32 v78, v167
	v_mov_b32_e32 v79, v167
	v_readlane_b32 s74, v248, 32
	v_readlane_b32 s75, v248, 33
	s_waitcnt vmcnt(11)
	v_mul_f32_e32 v6, v4, v5
	ds_bpermute_b32 v6, v158, v6
	s_waitcnt vmcnt(9)
	v_mul_f32_e32 v1, v2, v0
	ds_bpermute_b32 v1, v158, v1
	s_waitcnt lgkmcnt(1)
	v_fmac_f32_e32 v6, v4, v5
	s_waitcnt lgkmcnt(0)
	v_fmac_f32_e32 v1, v2, v0
	v_xor_b32_e32 v0, 16, v215
	v_cmp_lt_i32_e32 vcc, v0, v3
	s_nop 1
	v_cndmask_b32_e32 v0, v215, v0, vcc
	v_lshlrev_b32_e32 v0, 2, v0
	ds_bpermute_b32 v2, v0, v6
	ds_bpermute_b32 v0, v0, v1
	s_waitcnt lgkmcnt(1)
	v_add_f32_e32 v2, v6, v2
	s_waitcnt lgkmcnt(0)
	v_add_f32_e32 v0, v1, v0
	v_xor_b32_e32 v1, 8, v215
	v_cmp_lt_i32_e32 vcc, v1, v3
	s_nop 1
	v_cndmask_b32_e32 v1, v215, v1, vcc
	v_lshlrev_b32_e32 v1, 2, v1
	ds_bpermute_b32 v4, v1, v2
	ds_bpermute_b32 v1, v1, v0
	s_waitcnt lgkmcnt(1)
	v_add_f32_e32 v2, v2, v4
	s_waitcnt lgkmcnt(0)
	v_add_f32_e32 v0, v0, v1
	v_xor_b32_e32 v1, 4, v215
	v_cmp_lt_i32_e32 vcc, v1, v3
	s_nop 1
	v_cndmask_b32_e32 v1, v215, v1, vcc
	v_lshlrev_b32_e32 v1, 2, v1
	ds_bpermute_b32 v4, v1, v2
	ds_bpermute_b32 v1, v1, v0
	s_waitcnt lgkmcnt(1)
	v_add_f32_e32 v2, v2, v4
	s_waitcnt lgkmcnt(0)
	v_add_f32_e32 v0, v0, v1
	v_xor_b32_e32 v1, 2, v215
	v_cmp_lt_i32_e32 vcc, v1, v3
	s_nop 1
	v_cndmask_b32_e32 v1, v215, v1, vcc
	v_lshlrev_b32_e32 v1, 2, v1
	ds_bpermute_b32 v4, v1, v2
	ds_bpermute_b32 v1, v1, v0
	s_waitcnt lgkmcnt(1)
	v_add_f32_e32 v163, v2, v4
	s_waitcnt lgkmcnt(0)
	v_add_f32_e32 v165, v0, v1
	v_xor_b32_e32 v0, 1, v215
	v_cmp_lt_i32_e32 vcc, v0, v3
	s_nop 1
	v_cndmask_b32_e32 v0, v215, v0, vcc
	v_lshlrev_b32_e32 v0, 2, v0
	ds_bpermute_b32 v164, v0, v163
	ds_bpermute_b32 v166, v0, v165
	s_waitcnt vmcnt(8)
; DI float bf2f(unsigned v) { return __uint_as_float(v << 16); }
; DI f32x16 zero16() { f32x16 z; for (int i = 0; i < 16; ++i) z[i] = 0.f; return z; }
; DI void attn_item(const P& p, int l, int item, char* smem) {
;     ...
;     float q2 = 0.f;
; #pragma unroll
;     for (int ks = 0; ks < 4; ++ks) {
;       qf[ks] = *(const bf16x8*)(p.Qb + ((size_t)((bh * 2 + c) * SEQ + tq)) * 64 + 16 * ks + 8 * g);
; #pragma unroll
;       for (int j = 0; j < 8; ++j) { const float v = bf2f((unsigned)(u16)qf[ks][j]); q2 += v * v; }
;     }
;     q2 += __shfl_xor(q2, 32);
;     const float k2 = __uint_as_float(p.kmax[bh * 2 + c]);
;     negm = -(sqrtf(q2 * k2) * 1.01f + 1e-3f);
;   }
;   f32x16 O[4];
; #pragma unroll
;   for (int eb = 0; eb < 4; ++eb) O[eb] = zero16();
;   float ls = 0.f;
;   u32x4 kreg[2], vreg[2];
;   const u16* kbase = p.Kb + (size_t)(bh * 2) * SEQ * 64;
;   const u16* vbase = p.VT + (size_t)(bh * 128) * VTP;
; #pragma unroll
;   for (int i = 0; i < 2; ++i) kreg[i] = *(const u32x4*)(kbase + ((size_t)i * SEQ) * 64 + tid * 8);
; #pragma unroll
;   for (int i = 0; i < 2; ++i) {
;     const int cid = tid + NT * i;
;     const int e = cid >> 3, kc = cid & 7;
;     vreg[i] = *(const u32x4*)(vbase + (size_t)e * VTP + kc * 8);
;   }
;   for (int kt = -1; kt < 128; ++kt) {
;     if (kt + 1 < 128) {
;       u16* Kd = Ks + ((kt + 1) & 1) * (256 * 72);
;       u16* Vd = Kd + 2 * 64 * 72;
; #pragma unroll
;       for (int i = 0; i < 2; ++i) {
;         const int row = tid >> 3, kc = tid & 7;
;         *(u32x4*)(Kd + (i * 64 + row) * 72 + kc * 8) = kreg[i];
;       }
; #pragma unroll
;       for (int i = 0; i < 2; ++i) {
;         const int cid = tid + NT * i;
;         const int e = cid >> 3, kc = cid & 7;
;         uint2 w0; w0.x = vreg[i][0]; w0.y = vreg[i][1];
;         uint2 w1; w1.x = vreg[i][2]; w1.y = vreg[i][3];
;         u16* vd = Vd + e * 72 + (kc >> 1) * 16 + (kc & 1) * 4;
;         *(uint2*)vd = w0;
;         *(uint2*)(vd + 8) = w1;
;       }
;     }
;     if (kt + 2 < 128) {
;       const int kn = kt + 2;
; #pragma unroll
;       for (int i = 0; i < 2; ++i) kreg[i] = *(const u32x4*)(kbase + ((size_t)i * SEQ + kn * 64) * 64 + tid * 8);
; #pragma unroll
;       for (int i = 0; i < 2; ++i) {
;         const int cid = tid + NT * i;
;         const int e = cid >> 3, kc = cid & 7;
;         vreg[i] = *(const u32x4*)(vbase + (size_t)e * VTP + kn * 64 + kc * 8);
;       }
	v_and_b32_e32 v3, 0xffff0000, v112
	v_lshlrev_b32_e32 v2, 16, v112
	v_mul_f32_e32 v3, v3, v3
	v_fmac_f32_e32 v3, v2, v2
	v_lshlrev_b32_e32 v2, 16, v113
	v_fmac_f32_e32 v3, v2, v2
	v_and_b32_e32 v2, 0xffff0000, v113
	v_fmac_f32_e32 v3, v2, v2
	v_lshlrev_b32_e32 v2, 16, v114
	v_fmac_f32_e32 v3, v2, v2
	v_and_b32_e32 v2, 0xffff0000, v114
	v_fmac_f32_e32 v3, v2, v2
	v_lshlrev_b32_e32 v2, 16, v115
	v_fmac_f32_e32 v3, v2, v2
	v_and_b32_e32 v2, 0xffff0000, v115
	v_fmac_f32_e32 v3, v2, v2
	s_waitcnt vmcnt(7)
	v_lshlrev_b32_e32 v2, 16, v116
	v_fmac_f32_e32 v3, v2, v2
	v_and_b32_e32 v2, 0xffff0000, v116
	v_fmac_f32_e32 v3, v2, v2
	v_lshlrev_b32_e32 v2, 16, v117
	v_fmac_f32_e32 v3, v2, v2
	v_and_b32_e32 v2, 0xffff0000, v117
	v_fmac_f32_e32 v3, v2, v2
	v_lshlrev_b32_e32 v2, 16, v118
	v_fmac_f32_e32 v3, v2, v2
	v_and_b32_e32 v2, 0xffff0000, v118
	v_fmac_f32_e32 v3, v2, v2
	v_lshlrev_b32_e32 v2, 16, v119
	v_fmac_f32_e32 v3, v2, v2
	v_and_b32_e32 v2, 0xffff0000, v119
	v_fmac_f32_e32 v3, v2, v2
	s_waitcnt vmcnt(6)
	v_lshlrev_b32_e32 v2, 16, v124
	v_fmac_f32_e32 v3, v2, v2
	v_and_b32_e32 v2, 0xffff0000, v124
	v_fmac_f32_e32 v3, v2, v2
	v_lshlrev_b32_e32 v2, 16, v125
	v_fmac_f32_e32 v3, v2, v2
	v_and_b32_e32 v2, 0xffff0000, v125
	v_fmac_f32_e32 v3, v2, v2
	v_lshlrev_b32_e32 v2, 16, v126
	v_fmac_f32_e32 v3, v2, v2
	v_and_b32_e32 v2, 0xffff0000, v126
	v_fmac_f32_e32 v3, v2, v2
	v_lshlrev_b32_e32 v2, 16, v127
	v_fmac_f32_e32 v3, v2, v2
	v_and_b32_e32 v2, 0xffff0000, v127
	v_fmac_f32_e32 v3, v2, v2
	s_waitcnt vmcnt(5)
	v_lshlrev_b32_e32 v0, 16, v120
	v_fmac_f32_e32 v3, v0, v0
	v_and_b32_e32 v0, 0xffff0000, v120
	v_fmac_f32_e32 v3, v0, v0
	v_and_b32_e32 v1, 0xffff0000, v121
	v_lshlrev_b32_e32 v0, 16, v121
	v_pk_mul_f32 v[0:1], v[0:1], v[0:1]
	s_nop 0
	v_add_f32_e32 v0, v0, v3
	v_add_f32_e32 v2, v1, v0
	v_and_b32_e32 v1, 0xffff0000, v122
	v_lshlrev_b32_e32 v0, 16, v122
	v_pk_mul_f32 v[0:1], v[0:1], v[0:1]
	s_nop 0
	v_add_f32_e32 v0, v0, v2
	v_add_f32_e32 v2, v1, v0
	v_and_b32_e32 v1, 0xffff0000, v123
	v_lshlrev_b32_e32 v0, 16, v123
	v_pk_mul_f32 v[0:1], v[0:1], v[0:1]
	s_nop 0
	v_add_f32_e32 v0, v0, v2
	v_add_f32_e32 v0, v1, v0
	ds_bpermute_b32 v1, v158, v0
	s_waitcnt lgkmcnt(0)
	v_add_f32_e32 v2, v0, v1
	s_mov_b32 s6, 0xf800000
	s_waitcnt vmcnt(4)
	v_mul_f32_e32 v0, v14, v2
	v_cmp_gt_f32_e32 vcc, s6, v0
	v_mul_f32_e32 v1, 0x4f800000, v0
	s_nop 0
	v_cndmask_b32_e32 v0, v0, v1, vcc
	v_sqrt_f32_e32 v1, v0
	s_nop 0
	v_add_u32_e32 v2, -1, v1
	v_fma_f32 v3, -v2, v1, v0
	v_cmp_ge_f32_e64 s[6:7], 0, v3
	v_add_u32_e32 v3, 1, v1
	s_nop 0
	v_cndmask_b32_e64 v2, v1, v2, s[6:7]
	v_fma_f32 v1, -v3, v1, v0
	v_cmp_lt_f32_e64 s[6:7], 0, v1
	s_nop 1
	v_cndmask_b32_e64 v1, v2, v3, s[6:7]
	v_mul_f32_e32 v2, 0x37800000, v1
	v_cndmask_b32_e32 v1, v1, v2, vcc
	v_cmp_class_f32_e32 vcc, v0, v208
	s_nop 0
	s_nop 0
	v_cndmask_b32_e32 v0, v1, v0, vcc
	v_fmamk_f32 v2, v0, 0x3f8147ae, v209
	v_xor_b32_e32 v16, 0x80000000, v2
	v_add_u32_e32 v28, 0, v142
	v_add_u32_e32 v168, v28, v170
	v_lshlrev_b32_e32 v171, 1, v26
	v_lshlrev_b32_e32 v172, 1, v27
	s_waitcnt vmcnt(0)
	ds_write_b128 v168, v[92:95]
	ds_write_b128 v168, v[88:91] offset:9216
	v_add3_u32 v8, 0, v171, v172
	v_add_u32_e32 v169, v8, v170
	v_mul_lo_u32 v173, v25, s94
	v_add_u32_e32 v9, 0x4800, v169
	v_add_u32_e32 v143, v8, v173
	ds_write2_b64 v9, v[84:85], v[86:87] offset1:2
	v_add_u32_e32 v4, 0x4800, v143
	ds_write2_b64 v4, v[80:81], v[82:83] offset1:2
	v_add_co_u32_e32 v0, vcc, s65, v22
	s_mov_b32 s6, 0x102000
	s_nop 0
	v_addc_co_u32_e32 v1, vcc, 0, v23, vcc
	global_load_dwordx4 v[228:231], v[0:1], off
	v_add_co_u32_e32 v0, vcc, s6, v22
	v_lshlrev_b32_e32 v2, 4, v161
	s_nop 0
	v_addc_co_u32_e32 v1, vcc, 0, v23, vcc
	global_load_dwordx4 v[232:235], v[0:1], off
	global_load_dwordx4 v[236:239], v[20:21], off offset:128
	global_load_dwordx4 v[240:243], v[18:19], off offset:128
	v_lshl_or_b32 v0, v160, 6, v17
	v_mul_lo_u32 v175, v0, s94
	v_mad_u64_u32 v[0:1], s[6:7], s13, v219, v[36:37]
	v_and_b32_e32 v2, 0x70, v2
	v_or_b32_e32 v0, v0, v2
	v_lshl_add_u64 v[144:145], s[70:71], 0, v[0:1]
	v_mad_u64_u32 v[0:1], s[6:7], s13, v219, v[34:35]
	v_readlane_b32 s6, v248, 42
	s_add_u32 s6, s6, s11
	v_readlane_b32 s7, v248, 43
	v_or_b32_e32 v0, v0, v2
	s_addc_u32 s7, s7, 0
	v_mov_b32_e32 v17, v16
	v_mov_b32_e32 v18, v16
	v_mov_b32_e32 v19, v16
	v_mov_b32_e32 v20, v16
	v_mov_b32_e32 v21, v16
	v_mov_b32_e32 v22, v16
	v_mov_b32_e32 v23, v16
	v_mov_b32_e32 v24, v16
	v_mov_b32_e32 v25, v16
	v_mov_b32_e32 v26, v16
	v_mov_b32_e32 v27, v16
	v_mov_b32_e32 v28, v16
	v_mov_b32_e32 v29, v16
	v_mov_b32_e32 v30, v16
	v_mov_b32_e32 v31, v16
	v_lshl_add_u64 v[146:147], s[70:71], 0, v[0:1]
	v_lshl_add_u64 v[148:149], s[6:7], 0, v[32:33]
	v_mov_b32_e32 v0, 0
	v_mov_b32_e32 v1, v167
	v_mov_b32_e32 v2, v167
	v_mov_b32_e32 v3, v167
	v_mov_b32_e32 v4, v167
	v_mov_b32_e32 v5, v167
	v_mov_b32_e32 v6, v167
	v_mov_b32_e32 v7, v167
	v_mov_b32_e32 v8, v167
	v_mov_b32_e32 v9, v167
	v_mov_b32_e32 v10, v167
	v_mov_b32_e32 v11, v167
	v_mov_b32_e32 v12, v167
	v_mov_b32_e32 v13, v167
	v_mov_b32_e32 v14, v167
	v_mov_b32_e32 v15, v167
	v_mov_b32_e32 v32, 0
	v_mov_b32_e32 v33, v167
	v_mov_b32_e32 v34, v167
	v_mov_b32_e32 v35, v167
	v_mov_b32_e32 v36, v167
	v_mov_b32_e32 v37, v167
	s_waitcnt lgkmcnt(0)
	s_barrier
; #define MFMA(a, b, c) __builtin_amdgcn_mfma_f32_32x32x16_bf16((a), (b), (c), 0, 0, 0)
; DI void attn_item(const P& p, int l, int item, char* smem) {
;     ...
;     if (kt + 2 < 128) {
;       const int kn = kt + 2;
; #pragma unroll
;       for (int i = 0; i < 2; ++i) kreg[i] = *(const u32x4*)(kbase + ((size_t)i * SEQ + kn * 64) * 64 + tid * 8);
; #pragma unroll
;       for (int i = 0; i < 2; ++i) {
;         const int cid = tid + NT * i;
;         const int e = cid >> 3, kc = cid & 7;
;         vreg[i] = *(const u32x4*)(vbase + (size_t)e * VTP + kn * 64 + kc * 8);
;       }
;     }
;     __builtin_amdgcn_sched_barrier(0x38F);
;     if (kt >= 0) {
;       const u16* Kc = Ks + (kt & 1) * (256 * 72);
;       const u16* Vc = Kc + 2 * 64 * 72;
;       bf16x8 kf[8];
; #pragma unroll
;       for (int i = 0; i < 8; ++i)
;         kf[i] = *(const bf16x8*)(Kc + (c * 64 + 32 * (i & 1) + li) * 72 + 16 * (i >> 1) + 8 * g);
;       u32x4 vf[16];
; #pragma unroll
;       for (int i = 0; i < 16; ++i) {
;         const int eb = i & 3, s = (i >> 2) & 1, kb = i >> 3;
;         vf[i] = *(const u32x4*)(Vc + (32 * eb + li) * 72 + 32 * kb + 16 * s + 8 * g);
;       }
;       f32x16 S[2];
; #pragma unroll
;       for (int kb = 0; kb < 2; ++kb)
; #pragma unroll
;         for (int r = 0; r < 16; ++r) S[kb][r] = negm;
; #pragma unroll
;       for (int i = 0; i < 8; ++i) S[i & 1] = MFMA(kf[i], qf[i >> 1], S[i & 1]);
;       u32x4 pk[4];
;       float sum = 0.f;
; #pragma unroll
;       for (int ch = 0; ch < 4; ++ch) {
;         const int kb = ch >> 1, s = ch & 1;
; #pragma unroll
;         for (int j2 = 0; j2 < 4; ++j2) {
;           const float p0 = __builtin_amdgcn_exp2f(S[kb][8 * s + 2 * j2]);
;           const float p1 = __builtin_amdgcn_exp2f(S[kb][8 * s + 2 * j2 + 1]);
;           sum += p0 + p1;
;           pk[ch][j2] = pack2(p0, p1);
;         }
;       }
;       ls += sum;
; #pragma unroll
;       for (int i = 0; i < 16; ++i) {
;         const int eb = i & 3, ch = i >> 2;
;         O[eb] = MFMA(__builtin_bit_cast(bf16x8, vf[i]), __builtin_bit_cast(bf16x8, pk[ch]), O[eb]);
;       }
;     }
	v_readfirstlane_b32 s98, v148
	v_readfirstlane_b32 s99, v149
	v_readfirstlane_b32 s100, v146
	v_readfirstlane_b32 s101, v147
	v_add_u32_e32 v150, v175, v188
	v_add_u32_e32 v151, v174, v188
	v_subrev_u32_e32 v156, s98, v148
	v_subrev_u32_e32 v146, s100, v146
	v_subrev_u32_e32 v144, s100, v144
	s_sub_u32 s98, s98, 0x100000
	s_subb_u32 s99, s99, 0
	v_add_u32_e32 v148, 0x100000, v156
	v_add_u32_e32 v151, 0x4800, v151
	s_mov_b64 s[14:15], 0x2000
	v_mov_b32_e32 v190, 0
	v_mov_b32_e32 v191, 0
	v_mov_b32_e32 v196, 0
	s_movk_i32 s10, 63
	ds_read_b128 v[128:131], v150 offset:0
	ds_read_b128 v[132:135], v150 offset:32
	ds_read_b128 v[136:139], v150 offset:64
	ds_read_b128 v[152:155], v150 offset:96
	ds_read_b128 v[224:227], v150 offset:4608
	ds_read_b128 v[244:247], v150 offset:4640
	s_waitcnt lgkmcnt(4)
	v_mfma_f32_32x32x16_bf16 v[96:111], v[128:131], v[112:115], v[16:31]
	ds_read_b128 v[128:131], v150 offset:4672
	v_mfma_f32_32x32x16_bf16 v[96:111], v[132:135], v[116:119], v[96:111]
	ds_read_b128 v[132:135], v150 offset:4704
	s_waitcnt lgkmcnt(4)
	v_mfma_f32_32x32x16_bf16 v[96:111], v[136:139], v[124:127], v[96:111]
	ds_read_b128 v[136:139], v151 offset:0
	v_mfma_f32_32x32x16_bf16 v[96:111], v[152:155], v[120:123], v[96:111]
	ds_read_b128 v[152:155], v151 offset:4608
	s_waitcnt lgkmcnt(4)
	v_mfma_f32_32x32x16_bf16 v[80:95], v[224:227], v[112:115], v[16:31]
	ds_read_b128 v[224:227], v151 offset:9216
	v_mfma_f32_32x32x16_bf16 v[80:95], v[244:247], v[116:119], v[80:95]
	ds_read_b128 v[244:247], v151 offset:13824
	s_nop 6
	v_exp_f32_e32 v96, v96
	v_exp_f32_e32 v97, v97
	s_waitcnt lgkmcnt(4)
	v_mfma_f32_32x32x16_bf16 v[80:95], v[128:131], v[124:127], v[80:95]
	ds_read_b128 v[128:131], v151 offset:32
	v_exp_f32_e32 v98, v98
	v_exp_f32_e32 v99, v99
	v_exp_f32_e32 v100, v100
	v_mfma_f32_32x32x16_bf16 v[80:95], v[132:135], v[120:123], v[80:95]
	ds_read_b128 v[132:135], v151 offset:4640
	v_exp_f32_e32 v101, v101
	v_exp_f32_e32 v102, v102
	v_exp_f32_e32 v103, v103
	v_add_f32_e32 v167, v167, v96
	v_add_f32_e32 v190, v190, v97
	v_add_f32_e32 v191, v191, v98
	v_cvt_pk_bf16_f32 v176, v96, v97
	v_cvt_pk_bf16_f32 v177, v98, v99
	v_cvt_pk_bf16_f32 v178, v100, v101
	v_cvt_pk_bf16_f32 v179, v102, v103
	v_add_f32_e32 v196, v196, v99
	v_add_f32_e32 v167, v167, v100
	v_add_f32_e32 v190, v190, v101
	v_add_f32_e32 v191, v191, v102
	v_add_f32_e32 v196, v196, v103
.Lat_loop:
	s_waitcnt lgkmcnt(4)
	v_mfma_f32_32x32x16_bf16 v[64:79], v[136:139], v[176:179], v[64:79]
	ds_read_b128 v[136:139], v151 offset:9248
	v_exp_f32_e64 v104, v104
	v_exp_f32_e32 v105, v105
	v_mfma_f32_32x32x16_bf16 v[48:63], v[152:155], v[176:179], v[48:63]
	ds_read_b128 v[152:155], v151 offset:13856
	v_exp_f32_e64 v106, v106
	v_exp_f32_e32 v107, v107
	v_cvt_pk_bf16_f32 v180, v104, v105
	s_waitcnt lgkmcnt(4)
	v_mfma_f32_32x32x16_bf16 v[32:47], v[224:227], v[176:179], v[32:47]
	ds_read_b128 v[224:227], v151 offset:64
	v_exp_f32_e64 v108, v108
	v_exp_f32_e64 v109, v109
	v_cvt_pk_bf16_f32 v181, v106, v107
	v_mfma_f32_32x32x16_bf16 v[0:15], v[244:247], v[176:179], v[0:15]
	ds_read_b128 v[244:247], v151 offset:4672
	v_exp_f32_e64 v110, v110
	v_exp_f32_e64 v111, v111
	v_cvt_pk_bf16_f32 v182, v108, v109
	v_cvt_pk_bf16_f32 v183, v110, v111
	s_nop 0
	s_waitcnt lgkmcnt(4)
	v_mfma_f32_32x32x16_bf16 v[64:79], v[128:131], v[180:183], v[64:79]
	ds_read_b128 v[128:131], v151 offset:9280
	v_exp_f32_e64 v80, v80
	v_exp_f32_e64 v81, v81
	v_mfma_f32_32x32x16_bf16 v[48:63], v[132:135], v[180:183], v[48:63]
	ds_read_b128 v[132:135], v151 offset:13888
	v_exp_f32_e64 v82, v82
	v_exp_f32_e32 v83, v83
	v_cvt_pk_bf16_f32 v184, v80, v81
	s_waitcnt lgkmcnt(4)
	v_mfma_f32_32x32x16_bf16 v[32:47], v[136:139], v[180:183], v[32:47]
	ds_read_b128 v[136:139], v151 offset:96
	v_exp_f32_e64 v84, v84
	v_exp_f32_e64 v85, v85
	v_cvt_pk_bf16_f32 v185, v82, v83
	v_mfma_f32_32x32x16_bf16 v[0:15], v[152:155], v[180:183], v[0:15]
	ds_read_b128 v[152:155], v151 offset:4704
	v_exp_f32_e64 v86, v86
	v_exp_f32_e64 v87, v87
	v_cvt_pk_bf16_f32 v186, v84, v85
	v_cvt_pk_bf16_f32 v187, v86, v87
	s_nop 0
	s_waitcnt lgkmcnt(4)
	v_mfma_f32_32x32x16_bf16 v[64:79], v[224:227], v[184:187], v[64:79]
	ds_read_b128 v[224:227], v151 offset:9312
	v_exp_f32_e64 v88, v88
	v_exp_f32_e64 v89, v89
	v_mfma_f32_32x32x16_bf16 v[48:63], v[244:247], v[184:187], v[48:63]
	ds_read_b128 v[244:247], v151 offset:13920
	v_exp_f32_e64 v90, v90
	v_exp_f32_e32 v91, v91
	v_cvt_pk_bf16_f32 v192, v88, v89
	s_waitcnt lgkmcnt(4)
	v_mfma_f32_32x32x16_bf16 v[32:47], v[128:131], v[184:187], v[32:47]
	v_exp_f32_e64 v92, v92
	v_exp_f32_e32 v93, v93
	v_cvt_pk_bf16_f32 v193, v90, v91
	s_waitcnt vmcnt(0)
	ds_write_b128 v168, v[228:231] offset:36864
	ds_write_b128 v168, v[232:235] offset:46080
	v_mfma_f32_32x32x16_bf16 v[0:15], v[132:135], v[184:187], v[0:15]
	v_exp_f32_e64 v94, v94
	v_exp_f32_e32 v95, v95
	v_cvt_pk_bf16_f32 v194, v92, v93
	v_cvt_pk_bf16_f32 v195, v94, v95
	s_nop 0
	ds_write_b64 v169, v[236:237] offset:55296
	ds_write_b64 v169, v[238:239] offset:55312
	s_waitcnt lgkmcnt(6)
	v_mfma_f32_32x32x16_bf16 v[64:79], v[136:139], v[192:195], v[64:79]
	v_add_f32_e64 v167, v167, v104
	v_add_f32_e64 v190, v190, v105
	v_add_f32_e64 v191, v191, v106
	v_add_f32_e32 v196, v196, v107
	ds_write_b64 v143, v[240:241] offset:55296
	ds_write_b64 v143, v[242:243] offset:55312
	v_mfma_f32_32x32x16_bf16 v[48:63], v[152:155], v[192:195], v[48:63]
	v_add_f32_e64 v167, v167, v108
	v_add_f32_e64 v190, v190, v109
	v_add_f32_e64 v191, v191, v110
	v_add_f32_e32 v196, v196, v111
	s_waitcnt lgkmcnt(6)
	v_mfma_f32_32x32x16_bf16 v[32:47], v[224:227], v[192:195], v[32:47]
	v_add_f32_e64 v167, v167, v80
	v_add_f32_e64 v190, v190, v81
	v_add_f32_e64 v191, v191, v82
	v_add_f32_e64 v196, v196, v83
	v_mfma_f32_32x32x16_bf16 v[0:15], v[244:247], v[192:195], v[0:15]
	v_add_f32_e64 v167, v167, v84
	v_add_f32_e64 v190, v190, v85
	v_add_f32_e64 v191, v191, v86
	v_add_f32_e64 v196, v196, v87
	s_waitcnt lgkmcnt(0)
	s_barrier
; #define MFMA(a, b, c) __builtin_amdgcn_mfma_f32_32x32x16_bf16((a), (b), (c), 0, 0, 0)
; DI void attn_item(const P& p, int l, int item, char* smem) {
;     ...
;     if (kt + 2 < 128) {
;       const int kn = kt + 2;
; #pragma unroll
;       for (int i = 0; i < 2; ++i) kreg[i] = *(const u32x4*)(kbase + ((size_t)i * SEQ + kn * 64) * 64 + tid * 8);
; #pragma unroll
;       for (int i = 0; i < 2; ++i) {
;         const int cid = tid + NT * i;
;         const int e = cid >> 3, kc = cid & 7;
;         vreg[i] = *(const u32x4*)(vbase + (size_t)e * VTP + kn * 64 + kc * 8);
;       }
;     }
;     __builtin_amdgcn_sched_barrier(0x38F);
;     if (kt >= 0) {
;       const u16* Kc = Ks + (kt & 1) * (256 * 72);
;       const u16* Vc = Kc + 2 * 64 * 72;
;       bf16x8 kf[8];
; #pragma unroll
;       for (int i = 0; i < 8; ++i)
;         kf[i] = *(const bf16x8*)(Kc + (c * 64 + 32 * (i & 1) + li) * 72 + 16 * (i >> 1) + 8 * g);
;       u32x4 vf[16];
; #pragma unroll
;       for (int i = 0; i < 16; ++i) {
;         const int eb = i & 3, s = (i >> 2) & 1, kb = i >> 3;
;         vf[i] = *(const u32x4*)(Vc + (32 * eb + li) * 72 + 32 * kb + 16 * s + 8 * g);
;       }
;       f32x16 S[2];
; #pragma unroll
;       for (int kb = 0; kb < 2; ++kb)
; #pragma unroll
;         for (int r = 0; r < 16; ++r) S[kb][r] = negm;
; #pragma unroll
;       for (int i = 0; i < 8; ++i) S[i & 1] = MFMA(kf[i], qf[i >> 1], S[i & 1]);
;       u32x4 pk[4];
;       float sum = 0.f;
; #pragma unroll
;       for (int ch = 0; ch < 4; ++ch) {
;         const int kb = ch >> 1, s = ch & 1;
; #pragma unroll
;         for (int j2 = 0; j2 < 4; ++j2) {
;           const float p0 = __builtin_amdgcn_exp2f(S[kb][8 * s + 2 * j2]);
;           const float p1 = __builtin_amdgcn_exp2f(S[kb][8 * s + 2 * j2 + 1]);
;           sum += p0 + p1;
;           pk[ch][j2] = pack2(p0, p1);
;         }
;       }
;       ls += sum;
; #pragma unroll
;       for (int i = 0; i < 16; ++i) {
;         const int eb = i & 3, ch = i >> 2;
;         O[eb] = MFMA(__builtin_bit_cast(bf16x8, vf[i]), __builtin_bit_cast(bf16x8, pk[ch]), O[eb]);
;       }
;     }
;     __syncthreads();
	ds_read_b128 v[128:131], v150 offset:36864
	ds_read_b128 v[132:135], v150 offset:36896
	ds_read_b128 v[136:139], v150 offset:36928
	ds_read_b128 v[152:155], v150 offset:36960
	ds_read_b128 v[224:227], v150 offset:41472
	ds_read_b128 v[244:247], v150 offset:41504
	global_load_dwordx4 v[232:235], v148, s[98:99]
	global_load_dwordx4 v[228:231], v156, s[98:99]
	global_load_dwordx4 v[236:239], v146, s[100:101]
	global_load_dwordx4 v[240:243], v144, s[100:101]
	s_waitcnt lgkmcnt(4)
	v_mfma_f32_32x32x16_bf16 v[96:111], v[128:131], v[112:115], v[16:31]
	ds_read_b128 v[128:131], v150 offset:41536
	v_add_f32_e64 v167, v167, v88
	v_add_f32_e32 v190, v190, v89
	v_mfma_f32_32x32x16_bf16 v[96:111], v[132:135], v[116:119], v[96:111]
	ds_read_b128 v[132:135], v150 offset:41568
	v_add_f32_e64 v191, v191, v90
	v_add_f32_e32 v196, v196, v91
	s_waitcnt lgkmcnt(4)
	v_mfma_f32_32x32x16_bf16 v[96:111], v[136:139], v[124:127], v[96:111]
	ds_read_b128 v[136:139], v151 offset:36864
	v_add_f32_e64 v167, v167, v92
	v_add_f32_e64 v190, v190, v93
	v_mfma_f32_32x32x16_bf16 v[96:111], v[152:155], v[120:123], v[96:111]
	ds_read_b128 v[152:155], v151 offset:41472
	v_add_f32_e64 v191, v191, v94
	v_add_f32_e32 v196, v196, v95
	s_add_u32 s98, s98, s14
	s_addc_u32 s99, s99, s15
	s_waitcnt lgkmcnt(4)
	v_mfma_f32_32x32x16_bf16 v[80:95], v[224:227], v[112:115], v[16:31]
	ds_read_b128 v[224:227], v151 offset:46080
	s_add_u32 s100, s100, s58
	s_addc_u32 s101, s101, s59
	v_mfma_f32_32x32x16_bf16 v[80:95], v[244:247], v[116:119], v[80:95]
	ds_read_b128 v[244:247], v151 offset:50688
	s_nop 2
	v_exp_f32_e64 v96, v96
	v_exp_f32_e64 v97, v97
	s_waitcnt lgkmcnt(4)
	v_mfma_f32_32x32x16_bf16 v[80:95], v[128:131], v[124:127], v[80:95]
	ds_read_b128 v[128:131], v151 offset:36896
	v_exp_f32_e64 v98, v98
	v_exp_f32_e64 v99, v99
	v_exp_f32_e64 v100, v100
	v_mfma_f32_32x32x16_bf16 v[80:95], v[132:135], v[120:123], v[80:95]
	ds_read_b128 v[132:135], v151 offset:41504
	v_exp_f32_e64 v101, v101
	v_exp_f32_e64 v102, v102
	v_exp_f32_e64 v103, v103
	v_add_f32_e64 v167, v167, v96
	v_add_f32_e64 v190, v190, v97
	v_add_f32_e64 v191, v191, v98
	v_cvt_pk_bf16_f32 v176, v96, v97
	v_cvt_pk_bf16_f32 v177, v98, v99
	v_cvt_pk_bf16_f32 v178, v100, v101
	v_cvt_pk_bf16_f32 v179, v102, v103
	v_add_f32_e64 v196, v196, v99
	v_add_f32_e64 v167, v167, v100
	v_add_f32_e64 v190, v190, v101
	v_add_f32_e64 v191, v191, v102
	v_add_f32_e32 v196, v196, v103
	s_waitcnt lgkmcnt(4)
	v_mfma_f32_32x32x16_bf16 v[64:79], v[136:139], v[176:179], v[64:79]
	ds_read_b128 v[136:139], v151 offset:46112
	v_exp_f32_e64 v104, v104
	v_exp_f32_e64 v105, v105
	v_mfma_f32_32x32x16_bf16 v[48:63], v[152:155], v[176:179], v[48:63]
	ds_read_b128 v[152:155], v151 offset:50720
	v_exp_f32_e64 v106, v106
	v_exp_f32_e32 v107, v107
	v_cvt_pk_bf16_f32 v180, v104, v105
	s_waitcnt lgkmcnt(4)
	v_mfma_f32_32x32x16_bf16 v[32:47], v[224:227], v[176:179], v[32:47]
	ds_read_b128 v[224:227], v151 offset:36928
	v_exp_f32_e64 v108, v108
	v_exp_f32_e64 v109, v109
	v_cvt_pk_bf16_f32 v181, v106, v107
	v_mfma_f32_32x32x16_bf16 v[0:15], v[244:247], v[176:179], v[0:15]
	ds_read_b128 v[244:247], v151 offset:41536
	v_exp_f32_e64 v110, v110
	v_exp_f32_e64 v111, v111
	v_cvt_pk_bf16_f32 v182, v108, v109
	v_cvt_pk_bf16_f32 v183, v110, v111
	s_nop 0
	s_waitcnt lgkmcnt(4)
	v_mfma_f32_32x32x16_bf16 v[64:79], v[128:131], v[180:183], v[64:79]
	ds_read_b128 v[128:131], v151 offset:46144
	v_exp_f32_e64 v80, v80
	v_exp_f32_e64 v81, v81
	v_mfma_f32_32x32x16_bf16 v[48:63], v[132:135], v[180:183], v[48:63]
	ds_read_b128 v[132:135], v151 offset:50752
	v_exp_f32_e64 v82, v82
	v_exp_f32_e32 v83, v83
	v_cvt_pk_bf16_f32 v184, v80, v81
	s_waitcnt lgkmcnt(4)
	v_mfma_f32_32x32x16_bf16 v[32:47], v[136:139], v[180:183], v[32:47]
	ds_read_b128 v[136:139], v151 offset:36960
	v_exp_f32_e64 v84, v84
	v_exp_f32_e64 v85, v85
	v_cvt_pk_bf16_f32 v185, v82, v83
	v_mfma_f32_32x32x16_bf16 v[0:15], v[152:155], v[180:183], v[0:15]
	ds_read_b128 v[152:155], v151 offset:41568
	v_exp_f32_e64 v86, v86
	v_exp_f32_e64 v87, v87
	v_cvt_pk_bf16_f32 v186, v84, v85
	v_cvt_pk_bf16_f32 v187, v86, v87
	s_nop 0
	s_waitcnt lgkmcnt(4)
	v_mfma_f32_32x32x16_bf16 v[64:79], v[224:227], v[184:187], v[64:79]
	ds_read_b128 v[224:227], v151 offset:46176
	v_exp_f32_e64 v88, v88
	v_exp_f32_e64 v89, v89
	v_mfma_f32_32x32x16_bf16 v[48:63], v[244:247], v[184:187], v[48:63]
	ds_read_b128 v[244:247], v151 offset:50784
	v_exp_f32_e64 v90, v90
	v_exp_f32_e32 v91, v91
	v_cvt_pk_bf16_f32 v192, v88, v89
	s_waitcnt lgkmcnt(4)
	v_mfma_f32_32x32x16_bf16 v[32:47], v[128:131], v[184:187], v[32:47]
	v_exp_f32_e64 v92, v92
	v_exp_f32_e32 v93, v93
	v_cvt_pk_bf16_f32 v193, v90, v91
	s_waitcnt vmcnt(0)
	ds_write_b128 v168, v[228:231] offset:0
	ds_write_b128 v168, v[232:235] offset:9216
	v_mfma_f32_32x32x16_bf16 v[0:15], v[132:135], v[184:187], v[0:15]
	v_exp_f32_e64 v94, v94
	v_exp_f32_e32 v95, v95
	v_cvt_pk_bf16_f32 v194, v92, v93
	v_cvt_pk_bf16_f32 v195, v94, v95
	s_nop 0
	ds_write_b64 v169, v[236:237] offset:18432
	ds_write_b64 v169, v[238:239] offset:18448
	s_waitcnt lgkmcnt(6)
	v_mfma_f32_32x32x16_bf16 v[64:79], v[136:139], v[192:195], v[64:79]
	v_add_f32_e64 v167, v167, v104
	v_add_f32_e64 v190, v190, v105
	v_add_f32_e64 v191, v191, v106
	v_add_f32_e32 v196, v196, v107
	ds_write_b64 v143, v[240:241] offset:18432
	ds_write_b64 v143, v[242:243] offset:18448
	v_mfma_f32_32x32x16_bf16 v[48:63], v[152:155], v[192:195], v[48:63]
	v_add_f32_e64 v167, v167, v108
	v_add_f32_e64 v190, v190, v109
	v_add_f32_e64 v191, v191, v110
	v_add_f32_e32 v196, v196, v111
	s_waitcnt lgkmcnt(6)
	v_mfma_f32_32x32x16_bf16 v[32:47], v[224:227], v[192:195], v[32:47]
	v_add_f32_e64 v167, v167, v80
	v_add_f32_e64 v190, v190, v81
	v_add_f32_e64 v191, v191, v82
	v_add_f32_e64 v196, v196, v83
	v_mfma_f32_32x32x16_bf16 v[0:15], v[244:247], v[192:195], v[0:15]
	v_add_f32_e64 v167, v167, v84
	v_add_f32_e64 v190, v190, v85
	v_add_f32_e64 v191, v191, v86
	v_add_f32_e32 v196, v196, v87
	s_waitcnt lgkmcnt(0)
	s_barrier
; #define MFMA(a, b, c) __builtin_amdgcn_mfma_f32_32x32x16_bf16((a), (b), (c), 0, 0, 0)
; DI void attn_item(const P& p, int l, int item, char* smem) {
;     ...
;     if (kt + 2 < 128) {
;       const int kn = kt + 2;
; #pragma unroll
;       for (int i = 0; i < 2; ++i) kreg[i] = *(const u32x4*)(kbase + ((size_t)i * SEQ + kn * 64) * 64 + tid * 8);
; #pragma unroll
;       for (int i = 0; i < 2; ++i) {
;         const int cid = tid + NT * i;
;         const int e = cid >> 3, kc = cid & 7;
;         vreg[i] = *(const u32x4*)(vbase + (size_t)e * VTP + kn * 64 + kc * 8);
;       }
;     }
;     __builtin_amdgcn_sched_barrier(0x38F);
;     if (kt >= 0) {
;       const u16* Kc = Ks + (kt & 1) * (256 * 72);
;       const u16* Vc = Kc + 2 * 64 * 72;
;       bf16x8 kf[8];
; #pragma unroll
;       for (int i = 0; i < 8; ++i)
;         kf[i] = *(const bf16x8*)(Kc + (c * 64 + 32 * (i & 1) + li) * 72 + 16 * (i >> 1) + 8 * g);
;       u32x4 vf[16];
; #pragma unroll
;       for (int i = 0; i < 16; ++i) {
;         const int eb = i & 3, s = (i >> 2) & 1, kb = i >> 3;
;         vf[i] = *(const u32x4*)(Vc + (32 * eb + li) * 72 + 32 * kb + 16 * s + 8 * g);
;       }
;       f32x16 S[2];
; #pragma unroll
;       for (int kb = 0; kb < 2; ++kb)
; #pragma unroll
;         for (int r = 0; r < 16; ++r) S[kb][r] = negm;
; #pragma unroll
;       for (int i = 0; i < 8; ++i) S[i & 1] = MFMA(kf[i], qf[i >> 1], S[i & 1]);
;       u32x4 pk[4];
;       float sum = 0.f;
; #pragma unroll
;       for (int ch = 0; ch < 4; ++ch) {
;         const int kb = ch >> 1, s = ch & 1;
; #pragma unroll
;         for (int j2 = 0; j2 < 4; ++j2) {
;           const float p0 = __builtin_amdgcn_exp2f(S[kb][8 * s + 2 * j2]);
;           const float p1 = __builtin_amdgcn_exp2f(S[kb][8 * s + 2 * j2 + 1]);
;           sum += p0 + p1;
;           pk[ch][j2] = pack2(p0, p1);
;         }
;       }
;       ls += sum;
; #pragma unroll
;       for (int i = 0; i < 16; ++i) {
;         const int eb = i & 3, ch = i >> 2;
;         O[eb] = MFMA(__builtin_bit_cast(bf16x8, vf[i]), __builtin_bit_cast(bf16x8, pk[ch]), O[eb]);
;       }
;     }
	s_add_i32 s10, s10, -1
	s_cmp_eq_u32 s10, 0
	s_cbranch_scc1 .Lat_exit
	ds_read_b128 v[128:131], v150 offset:0
	ds_read_b128 v[132:135], v150 offset:32
	ds_read_b128 v[136:139], v150 offset:64
	ds_read_b128 v[152:155], v150 offset:96
	ds_read_b128 v[224:227], v150 offset:4608
	ds_read_b128 v[244:247], v150 offset:4640
	global_load_dwordx4 v[232:235], v148, s[98:99]
	global_load_dwordx4 v[228:231], v156, s[98:99]
	global_load_dwordx4 v[236:239], v146, s[100:101]
	global_load_dwordx4 v[240:243], v144, s[100:101]
	s_waitcnt lgkmcnt(4)
	v_mfma_f32_32x32x16_bf16 v[96:111], v[128:131], v[112:115], v[16:31]
	ds_read_b128 v[128:131], v150 offset:4672
	v_add_f32_e64 v167, v167, v88
	v_add_f32_e32 v190, v190, v89
	v_mfma_f32_32x32x16_bf16 v[96:111], v[132:135], v[116:119], v[96:111]
	ds_read_b128 v[132:135], v150 offset:4704
	v_add_f32_e64 v191, v191, v90
	v_add_f32_e32 v196, v196, v91
	s_waitcnt lgkmcnt(4)
	v_mfma_f32_32x32x16_bf16 v[96:111], v[136:139], v[124:127], v[96:111]
	ds_read_b128 v[136:139], v151 offset:0
	v_add_f32_e64 v167, v167, v92
	v_add_f32_e64 v190, v190, v93
	v_mfma_f32_32x32x16_bf16 v[96:111], v[152:155], v[120:123], v[96:111]
	ds_read_b128 v[152:155], v151 offset:4608
	v_add_f32_e64 v191, v191, v94
	v_add_f32_e32 v196, v196, v95
	s_add_u32 s98, s98, s14
	s_addc_u32 s99, s99, s15
	s_waitcnt lgkmcnt(4)
	v_mfma_f32_32x32x16_bf16 v[80:95], v[224:227], v[112:115], v[16:31]
	ds_read_b128 v[224:227], v151 offset:9216
	s_add_u32 s100, s100, s58
	s_addc_u32 s101, s101, s59
	v_mfma_f32_32x32x16_bf16 v[80:95], v[244:247], v[116:119], v[80:95]
	ds_read_b128 v[244:247], v151 offset:13824
	s_nop 2
	v_exp_f32_e64 v96, v96
	v_exp_f32_e64 v97, v97
	s_waitcnt lgkmcnt(4)
	v_mfma_f32_32x32x16_bf16 v[80:95], v[128:131], v[124:127], v[80:95]
	ds_read_b128 v[128:131], v151 offset:32
	v_exp_f32_e64 v98, v98
	v_exp_f32_e64 v99, v99
	v_exp_f32_e64 v100, v100
	v_mfma_f32_32x32x16_bf16 v[80:95], v[132:135], v[120:123], v[80:95]
	ds_read_b128 v[132:135], v151 offset:4640
	v_exp_f32_e64 v101, v101
	v_exp_f32_e64 v102, v102
	v_exp_f32_e64 v103, v103
	v_add_f32_e64 v167, v167, v96
	v_add_f32_e64 v190, v190, v97
	v_add_f32_e64 v191, v191, v98
	v_cvt_pk_bf16_f32 v176, v96, v97
	v_cvt_pk_bf16_f32 v177, v98, v99
	v_cvt_pk_bf16_f32 v178, v100, v101
	v_cvt_pk_bf16_f32 v179, v102, v103
	v_add_f32_e64 v196, v196, v99
	v_add_f32_e64 v167, v167, v100
	v_add_f32_e64 v190, v190, v101
	v_add_f32_e64 v191, v191, v102
	v_add_f32_e64 v196, v196, v103
	s_branch .Lat_loop
.Lat_exit:
	ds_read_b128 v[128:131], v150 offset:0
	ds_read_b128 v[132:135], v150 offset:32
	ds_read_b128 v[136:139], v150 offset:64
	ds_read_b128 v[152:155], v150 offset:96
	ds_read_b128 v[224:227], v150 offset:4608
	ds_read_b128 v[244:247], v150 offset:4640
	global_load_dwordx4 v[232:235], v148, s[98:99]
	global_load_dwordx4 v[228:231], v156, s[98:99]
	global_load_dwordx4 v[236:239], v146, s[100:101]
	global_load_dwordx4 v[240:243], v144, s[100:101]
	s_waitcnt lgkmcnt(4)
	v_mfma_f32_32x32x16_bf16 v[96:111], v[128:131], v[112:115], v[16:31]
	ds_read_b128 v[128:131], v150 offset:4672
	v_add_f32_e32 v167, v167, v88
	v_add_f32_e32 v190, v190, v89
	v_mfma_f32_32x32x16_bf16 v[96:111], v[132:135], v[116:119], v[96:111]
	ds_read_b128 v[132:135], v150 offset:4704
	v_add_f32_e32 v191, v191, v90
	v_add_f32_e32 v196, v196, v91
	s_waitcnt lgkmcnt(4)
	v_mfma_f32_32x32x16_bf16 v[96:111], v[136:139], v[124:127], v[96:111]
	ds_read_b128 v[136:139], v151 offset:0
	v_add_f32_e32 v167, v167, v92
	v_add_f32_e32 v190, v190, v93
	v_mfma_f32_32x32x16_bf16 v[96:111], v[152:155], v[120:123], v[96:111]
	ds_read_b128 v[152:155], v151 offset:4608
	v_add_f32_e32 v191, v191, v94
	v_add_f32_e32 v196, v196, v95
	s_add_u32 s98, s98, s14
	s_addc_u32 s99, s99, s15
	s_waitcnt lgkmcnt(4)
	v_mfma_f32_32x32x16_bf16 v[80:95], v[224:227], v[112:115], v[16:31]
	ds_read_b128 v[224:227], v151 offset:9216
	s_add_u32 s100, s100, s58
	s_addc_u32 s101, s101, s59
	v_mfma_f32_32x32x16_bf16 v[80:95], v[244:247], v[116:119], v[80:95]
	ds_read_b128 v[244:247], v151 offset:13824
	s_nop 2
	v_exp_f32_e32 v96, v96
	v_exp_f32_e32 v97, v97
	s_waitcnt lgkmcnt(4)
	v_mfma_f32_32x32x16_bf16 v[80:95], v[128:131], v[124:127], v[80:95]
	ds_read_b128 v[128:131], v151 offset:32
	v_exp_f32_e32 v98, v98
	v_exp_f32_e32 v99, v99
	v_exp_f32_e32 v100, v100
	v_mfma_f32_32x32x16_bf16 v[80:95], v[132:135], v[120:123], v[80:95]
	ds_read_b128 v[132:135], v151 offset:4640
	v_exp_f32_e32 v101, v101
	v_exp_f32_e32 v102, v102
	v_exp_f32_e32 v103, v103
	v_add_f32_e32 v167, v167, v96
	v_add_f32_e32 v190, v190, v97
	v_add_f32_e32 v191, v191, v98
	v_cvt_pk_bf16_f32 v176, v96, v97
	v_cvt_pk_bf16_f32 v177, v98, v99
	v_cvt_pk_bf16_f32 v178, v100, v101
	v_cvt_pk_bf16_f32 v179, v102, v103
	v_add_f32_e32 v196, v196, v99
	v_add_f32_e32 v167, v167, v100
	v_add_f32_e32 v190, v190, v101
	v_add_f32_e32 v191, v191, v102
	v_add_f32_e32 v196, v196, v103
	s_waitcnt lgkmcnt(4)
	v_mfma_f32_32x32x16_bf16 v[64:79], v[136:139], v[176:179], v[64:79]
	ds_read_b128 v[136:139], v151 offset:9248
	v_exp_f32_e32 v104, v104
	v_exp_f32_e32 v105, v105
	v_mfma_f32_32x32x16_bf16 v[48:63], v[152:155], v[176:179], v[48:63]
	ds_read_b128 v[152:155], v151 offset:13856
	v_exp_f32_e32 v106, v106
	v_exp_f32_e32 v107, v107
	v_cvt_pk_bf16_f32 v180, v104, v105
	s_waitcnt lgkmcnt(4)
	v_mfma_f32_32x32x16_bf16 v[32:47], v[224:227], v[176:179], v[32:47]
	ds_read_b128 v[224:227], v151 offset:64
	v_exp_f32_e32 v108, v108
	v_exp_f32_e32 v109, v109
	v_cvt_pk_bf16_f32 v181, v106, v107
	v_mfma_f32_32x32x16_bf16 v[0:15], v[244:247], v[176:179], v[0:15]
	ds_read_b128 v[244:247], v151 offset:4672
	v_exp_f32_e32 v110, v110
	v_exp_f32_e32 v111, v111
	v_cvt_pk_bf16_f32 v182, v108, v109
	v_cvt_pk_bf16_f32 v183, v110, v111
	s_nop 0
	s_waitcnt lgkmcnt(4)
; #define MFMA(a, b, c) __builtin_amdgcn_mfma_f32_32x32x16_bf16((a), (b), (c), 0, 0, 0)
; DI void attn_item(const P& p, int l, int item, char* smem) {
;     ...
;     if (kt >= 0) {
;       const u16* Kc = Ks + (kt & 1) * (256 * 72);
;       const u16* Vc = Kc + 2 * 64 * 72;
;       bf16x8 kf[8];
; #pragma unroll
;       for (int i = 0; i < 8; ++i)
;         kf[i] = *(const bf16x8*)(Kc + (c * 64 + 32 * (i & 1) + li) * 72 + 16 * (i >> 1) + 8 * g);
;       u32x4 vf[16];
; #pragma unroll
;       for (int i = 0; i < 16; ++i) {
;         const int eb = i & 3, s = (i >> 2) & 1, kb = i >> 3;
;         vf[i] = *(const u32x4*)(Vc + (32 * eb + li) * 72 + 32 * kb + 16 * s + 8 * g);
;       }
;       f32x16 S[2];
; #pragma unroll
;       for (int kb = 0; kb < 2; ++kb)
; #pragma unroll
;         for (int r = 0; r < 16; ++r) S[kb][r] = negm;
; #pragma unroll
;       for (int i = 0; i < 8; ++i) S[i & 1] = MFMA(kf[i], qf[i >> 1], S[i & 1]);
;       u32x4 pk[4];
;       float sum = 0.f;
; #pragma unroll
;       for (int ch = 0; ch < 4; ++ch) {
;         const int kb = ch >> 1, s = ch & 1;
; #pragma unroll
;         for (int j2 = 0; j2 < 4; ++j2) {
;           const float p0 = __builtin_amdgcn_exp2f(S[kb][8 * s + 2 * j2]);
;           const float p1 = __builtin_amdgcn_exp2f(S[kb][8 * s + 2 * j2 + 1]);
;           sum += p0 + p1;
;           pk[ch][j2] = pack2(p0, p1);
;         }
;       }
;       ls += sum;
; #pragma unroll
;       for (int i = 0; i < 16; ++i) {
;         const int eb = i & 3, ch = i >> 2;
;         O[eb] = MFMA(__builtin_bit_cast(bf16x8, vf[i]), __builtin_bit_cast(bf16x8, pk[ch]), O[eb]);
;       }
;     }
;     __syncthreads();
	v_mfma_f32_32x32x16_bf16 v[64:79], v[128:131], v[180:183], v[64:79]
	ds_read_b128 v[128:131], v151 offset:9280
	v_exp_f32_e32 v80, v80
	v_exp_f32_e32 v81, v81
	v_mfma_f32_32x32x16_bf16 v[48:63], v[132:135], v[180:183], v[48:63]
	ds_read_b128 v[132:135], v151 offset:13888
	v_exp_f32_e32 v82, v82
	v_exp_f32_e32 v83, v83
	v_cvt_pk_bf16_f32 v184, v80, v81
	s_waitcnt lgkmcnt(4)
	v_mfma_f32_32x32x16_bf16 v[32:47], v[136:139], v[180:183], v[32:47]
	ds_read_b128 v[136:139], v151 offset:96
	v_exp_f32_e32 v84, v84
	v_exp_f32_e32 v85, v85
	v_cvt_pk_bf16_f32 v185, v82, v83
	v_mfma_f32_32x32x16_bf16 v[0:15], v[152:155], v[180:183], v[0:15]
	ds_read_b128 v[152:155], v151 offset:4704
	v_exp_f32_e32 v86, v86
	v_exp_f32_e32 v87, v87
	v_cvt_pk_bf16_f32 v186, v84, v85
	v_cvt_pk_bf16_f32 v187, v86, v87
	s_nop 0
	s_waitcnt lgkmcnt(4)
	v_mfma_f32_32x32x16_bf16 v[64:79], v[224:227], v[184:187], v[64:79]
	ds_read_b128 v[224:227], v151 offset:9312
	v_exp_f32_e32 v88, v88
	v_exp_f32_e32 v89, v89
	v_mfma_f32_32x32x16_bf16 v[48:63], v[244:247], v[184:187], v[48:63]
	ds_read_b128 v[244:247], v151 offset:13920
	v_exp_f32_e32 v90, v90
	v_exp_f32_e32 v91, v91
	v_cvt_pk_bf16_f32 v192, v88, v89
	s_waitcnt lgkmcnt(4)
	v_mfma_f32_32x32x16_bf16 v[32:47], v[128:131], v[184:187], v[32:47]
	v_exp_f32_e32 v92, v92
	v_exp_f32_e32 v93, v93
	v_cvt_pk_bf16_f32 v193, v90, v91
	s_waitcnt vmcnt(0)
	ds_write_b128 v168, v[228:231] offset:36864
	ds_write_b128 v168, v[232:235] offset:46080
	v_mfma_f32_32x32x16_bf16 v[0:15], v[132:135], v[184:187], v[0:15]
	v_exp_f32_e32 v94, v94
	v_exp_f32_e32 v95, v95
	v_cvt_pk_bf16_f32 v194, v92, v93
	v_cvt_pk_bf16_f32 v195, v94, v95
	s_nop 0
	ds_write_b64 v169, v[236:237] offset:55296
	ds_write_b64 v169, v[238:239] offset:55312
	s_waitcnt lgkmcnt(6)
	v_mfma_f32_32x32x16_bf16 v[64:79], v[136:139], v[192:195], v[64:79]
	v_add_f32_e32 v167, v167, v104
	v_add_f32_e32 v190, v190, v105
	v_add_f32_e32 v191, v191, v106
	v_add_f32_e32 v196, v196, v107
	ds_write_b64 v143, v[240:241] offset:55296
	ds_write_b64 v143, v[242:243] offset:55312
	v_mfma_f32_32x32x16_bf16 v[48:63], v[152:155], v[192:195], v[48:63]
	v_add_f32_e32 v167, v167, v108
	v_add_f32_e32 v190, v190, v109
	v_add_f32_e32 v191, v191, v110
	v_add_f32_e32 v196, v196, v111
	s_waitcnt lgkmcnt(6)
	v_mfma_f32_32x32x16_bf16 v[32:47], v[224:227], v[192:195], v[32:47]
	v_add_f32_e32 v167, v167, v80
	v_add_f32_e32 v190, v190, v81
	v_add_f32_e32 v191, v191, v82
	v_add_f32_e32 v196, v196, v83
	v_mfma_f32_32x32x16_bf16 v[0:15], v[244:247], v[192:195], v[0:15]
	v_add_f32_e32 v167, v167, v84
	v_add_f32_e32 v190, v190, v85
	v_add_f32_e32 v191, v191, v86
	v_add_f32_e32 v196, v196, v87
	s_waitcnt lgkmcnt(0)
	s_barrier
	ds_read_b128 v[128:131], v150 offset:36864
	ds_read_b128 v[132:135], v150 offset:36896
	ds_read_b128 v[136:139], v150 offset:36928
	ds_read_b128 v[152:155], v150 offset:36960
	ds_read_b128 v[224:227], v150 offset:41472
	ds_read_b128 v[244:247], v150 offset:41504
	s_waitcnt lgkmcnt(4)
	v_mfma_f32_32x32x16_bf16 v[96:111], v[128:131], v[112:115], v[16:31]
	ds_read_b128 v[128:131], v150 offset:41536
	v_add_f32_e32 v167, v167, v88
	v_add_f32_e32 v190, v190, v89
	v_mfma_f32_32x32x16_bf16 v[96:111], v[132:135], v[116:119], v[96:111]
	ds_read_b128 v[132:135], v150 offset:41568
	v_add_f32_e32 v191, v191, v90
	v_add_f32_e32 v196, v196, v91
	s_waitcnt lgkmcnt(4)
	v_mfma_f32_32x32x16_bf16 v[96:111], v[136:139], v[124:127], v[96:111]
	ds_read_b128 v[136:139], v151 offset:36864
	v_add_f32_e32 v167, v167, v92
	v_add_f32_e32 v190, v190, v93
	v_mfma_f32_32x32x16_bf16 v[96:111], v[152:155], v[120:123], v[96:111]
	ds_read_b128 v[152:155], v151 offset:41472
	v_add_f32_e32 v191, v191, v94
	v_add_f32_e32 v196, v196, v95
	s_waitcnt lgkmcnt(4)
	v_mfma_f32_32x32x16_bf16 v[80:95], v[224:227], v[112:115], v[16:31]
	ds_read_b128 v[224:227], v151 offset:46080
	v_mfma_f32_32x32x16_bf16 v[80:95], v[244:247], v[116:119], v[80:95]
	ds_read_b128 v[244:247], v151 offset:50688
	s_nop 6
	v_exp_f32_e32 v96, v96
	v_exp_f32_e32 v97, v97
	s_waitcnt lgkmcnt(4)
	v_mfma_f32_32x32x16_bf16 v[80:95], v[128:131], v[124:127], v[80:95]
	ds_read_b128 v[128:131], v151 offset:36896
	v_exp_f32_e32 v98, v98
	v_exp_f32_e32 v99, v99
	v_exp_f32_e32 v100, v100
	v_mfma_f32_32x32x16_bf16 v[80:95], v[132:135], v[120:123], v[80:95]
	ds_read_b128 v[132:135], v151 offset:41504
	v_exp_f32_e32 v101, v101
	v_exp_f32_e32 v102, v102
	v_exp_f32_e32 v103, v103
	v_add_f32_e32 v167, v167, v96
	v_add_f32_e32 v190, v190, v97
	v_add_f32_e32 v191, v191, v98
	v_cvt_pk_bf16_f32 v176, v96, v97
	v_cvt_pk_bf16_f32 v177, v98, v99
	v_cvt_pk_bf16_f32 v178, v100, v101
	v_cvt_pk_bf16_f32 v179, v102, v103
	v_add_f32_e32 v196, v196, v99
	v_add_f32_e32 v167, v167, v100
	v_add_f32_e32 v190, v190, v101
	v_add_f32_e32 v191, v191, v102
	v_add_f32_e32 v196, v196, v103
	s_waitcnt lgkmcnt(4)
	v_mfma_f32_32x32x16_bf16 v[64:79], v[136:139], v[176:179], v[64:79]
	ds_read_b128 v[136:139], v151 offset:46112
	v_exp_f32_e32 v104, v104
	v_exp_f32_e32 v105, v105
	v_mfma_f32_32x32x16_bf16 v[48:63], v[152:155], v[176:179], v[48:63]
	ds_read_b128 v[152:155], v151 offset:50720
	v_exp_f32_e32 v106, v106
	v_exp_f32_e32 v107, v107
	v_cvt_pk_bf16_f32 v180, v104, v105
	s_waitcnt lgkmcnt(4)
; #define MFMA(a, b, c) __builtin_amdgcn_mfma_f32_32x32x16_bf16((a), (b), (c), 0, 0, 0)
; DI void attn_item(const P& p, int l, int item, char* smem) {
;     ...
; #pragma unroll
;       for (int ch = 0; ch < 4; ++ch) {
;         const int kb = ch >> 1, s = ch & 1;
; #pragma unroll
;         for (int j2 = 0; j2 < 4; ++j2) {
;           const float p0 = __builtin_amdgcn_exp2f(S[kb][8 * s + 2 * j2]);
;           const float p1 = __builtin_amdgcn_exp2f(S[kb][8 * s + 2 * j2 + 1]);
;           sum += p0 + p1;
;           pk[ch][j2] = pack2(p0, p1);
;         }
;       }
;       ls += sum;
; #pragma unroll
;       for (int i = 0; i < 16; ++i) {
;         const int eb = i & 3, ch = i >> 2;
;         O[eb] = MFMA(__builtin_bit_cast(bf16x8, vf[i]), __builtin_bit_cast(bf16x8, pk[ch]), O[eb]);
;       }
;     }
;     __syncthreads();
;   }
;   const float lt = ls + __shfl_xor(ls, 32);
;   const float inv = (c == 0) ? (1.0f / lt) : (lam / lt);
;     ...
;   if (c == 0) {
;     float ss = 0.f;
; #pragma unroll
;     for (int eb = 0; eb < 4; ++eb)
; #pragma unroll
;       for (int r = 0; r < 16; ++r) {
;         const float o = O[eb][r] * inv - exch[(eb * 16 + r) * 64 + lane];
;         O[eb][r] = o;
;         ss += o * o;
;       }
;     ss += __shfl_xor(ss, 32);
;     const float rn = rsqrtf(ss * (1.0f / 128.0f) + 1e-5f) * (1.0f - lam_init);
;     const size_t tok = (size_t)b * SEQ + tq;
; #pragma unroll
;     for (int eb = 0; eb < 4; ++eb)
; #pragma unroll
;       for (int rq = 0; rq < 4; ++rq) {
;         const int e = 32 * eb + 8 * rq + 4 * g;
;         const uint2 gt = *(const uint2*)(p.AG + tok * 512 + h * 128 + e);
;         const float4 sg = *(const float4*)(p.subg + l * 128 + e);
	v_mfma_f32_32x32x16_bf16 v[32:47], v[224:227], v[176:179], v[32:47]
	ds_read_b128 v[224:227], v151 offset:36928
	v_exp_f32_e32 v108, v108
	v_exp_f32_e32 v109, v109
	v_cvt_pk_bf16_f32 v181, v106, v107
	v_mfma_f32_32x32x16_bf16 v[0:15], v[244:247], v[176:179], v[0:15]
	ds_read_b128 v[244:247], v151 offset:41536
	v_exp_f32_e32 v110, v110
	v_exp_f32_e32 v111, v111
	v_cvt_pk_bf16_f32 v182, v108, v109
	v_cvt_pk_bf16_f32 v183, v110, v111
	s_nop 0
	s_waitcnt lgkmcnt(4)
	v_mfma_f32_32x32x16_bf16 v[64:79], v[128:131], v[180:183], v[64:79]
	ds_read_b128 v[128:131], v151 offset:46144
	v_exp_f32_e32 v80, v80
	v_exp_f32_e32 v81, v81
	v_mfma_f32_32x32x16_bf16 v[48:63], v[132:135], v[180:183], v[48:63]
	ds_read_b128 v[132:135], v151 offset:50752
	v_exp_f32_e32 v82, v82
	v_exp_f32_e32 v83, v83
	v_cvt_pk_bf16_f32 v184, v80, v81
	s_waitcnt lgkmcnt(4)
	v_mfma_f32_32x32x16_bf16 v[32:47], v[136:139], v[180:183], v[32:47]
	ds_read_b128 v[136:139], v151 offset:36960
	v_exp_f32_e32 v84, v84
	v_exp_f32_e32 v85, v85
	v_cvt_pk_bf16_f32 v185, v82, v83
	v_mfma_f32_32x32x16_bf16 v[0:15], v[152:155], v[180:183], v[0:15]
	ds_read_b128 v[152:155], v151 offset:41568
	v_exp_f32_e32 v86, v86
	v_exp_f32_e32 v87, v87
	v_cvt_pk_bf16_f32 v186, v84, v85
	v_cvt_pk_bf16_f32 v187, v86, v87
	s_nop 0
	s_waitcnt lgkmcnt(4)
	v_mfma_f32_32x32x16_bf16 v[64:79], v[224:227], v[184:187], v[64:79]
	ds_read_b128 v[224:227], v151 offset:46176
	v_exp_f32_e32 v88, v88
	v_exp_f32_e32 v89, v89
	v_mfma_f32_32x32x16_bf16 v[48:63], v[244:247], v[184:187], v[48:63]
	ds_read_b128 v[244:247], v151 offset:50784
	v_exp_f32_e32 v90, v90
	v_exp_f32_e32 v91, v91
	v_cvt_pk_bf16_f32 v192, v88, v89
	s_waitcnt lgkmcnt(4)
	v_mfma_f32_32x32x16_bf16 v[32:47], v[128:131], v[184:187], v[32:47]
	v_exp_f32_e32 v92, v92
	v_exp_f32_e32 v93, v93
	v_cvt_pk_bf16_f32 v193, v90, v91
	v_mfma_f32_32x32x16_bf16 v[0:15], v[132:135], v[184:187], v[0:15]
	v_exp_f32_e32 v94, v94
	v_exp_f32_e32 v95, v95
	v_cvt_pk_bf16_f32 v194, v92, v93
	v_cvt_pk_bf16_f32 v195, v94, v95
	s_nop 0
	s_waitcnt lgkmcnt(2)
	v_mfma_f32_32x32x16_bf16 v[64:79], v[136:139], v[192:195], v[64:79]
	v_add_f32_e32 v167, v167, v104
	v_add_f32_e32 v190, v190, v105
	v_add_f32_e32 v191, v191, v106
	v_add_f32_e32 v196, v196, v107
	v_mfma_f32_32x32x16_bf16 v[48:63], v[152:155], v[192:195], v[48:63]
	v_add_f32_e32 v167, v167, v108
	v_add_f32_e32 v190, v190, v109
	v_add_f32_e32 v191, v191, v110
	v_add_f32_e32 v196, v196, v111
	s_waitcnt lgkmcnt(0)
	v_mfma_f32_32x32x16_bf16 v[32:47], v[224:227], v[192:195], v[32:47]
	v_add_f32_e32 v167, v167, v80
	v_add_f32_e32 v190, v190, v81
	v_add_f32_e32 v191, v191, v82
	v_add_f32_e32 v196, v196, v83
	v_mfma_f32_32x32x16_bf16 v[0:15], v[244:247], v[192:195], v[0:15]
	v_add_f32_e32 v167, v167, v84
	v_add_f32_e32 v190, v190, v85
	v_add_f32_e32 v191, v191, v86
	v_add_f32_e32 v196, v196, v87
	s_waitcnt lgkmcnt(0)
	s_barrier
	v_add_f32_e32 v167, v167, v88
	v_add_f32_e32 v190, v190, v89
	v_add_f32_e32 v191, v191, v90
	v_add_f32_e32 v196, v196, v91
	v_add_f32_e32 v167, v167, v92
	v_add_f32_e32 v190, v190, v93
	v_add_f32_e32 v191, v191, v94
	v_add_f32_e32 v196, v196, v95
	v_add_f32_e32 v167, v167, v190
	v_add_f32_e32 v191, v191, v196
	v_readlane_b32 s6, v248, 5
	v_add_f32_e32 v96, v165, v166
	v_add_f32_e32 v97, v163, v164
	v_mul_f32_e32 v96, 0x3fb8aa3b, v96
	v_mul_f32_e32 v97, 0x3fb8aa3b, v97
	v_exp_f32_e32 v139, v96
	v_exp_f32_e32 v17, v97
	v_add_f32_e32 v16, v167, v191
	ds_bpermute_b32 v18, v158, v16
	v_sub_f32_e32 v17, v17, v139
	v_add_f32_e32 v17, s6, v17
	s_movk_i32 s6, 0x100
	v_cmp_gt_u32_e64 s[6:7], s6, v161
	s_waitcnt lgkmcnt(0)
	v_add_f32_e32 v16, v16, v18
	s_nop 0
	v_cndmask_b32_e64 v17, v17, 1.0, s[6:7]
	v_div_scale_f32 v18, s[10:11], v16, v16, v17
	v_rcp_f32_e32 v19, v18
	s_nop 0
	v_fma_f32 v24, -v18, v19, 1.0
	s_nop 0
	v_fmac_f32_e32 v19, v24, v19
	v_div_scale_f32 v24, vcc, v17, v16, v17
	v_mul_f32_e32 v25, v24, v19
	v_fma_f32 v26, -v18, v25, v24
	v_fmac_f32_e32 v25, v26, v19
	v_fma_f32 v18, -v18, v25, v24
	s_nop 0
	v_div_fmas_f32 v18, v18, v19, v25
	v_div_fixup_f32 v80, v18, v16, v17
	v_lshl_add_u32 v16, v162, 14, 0
	v_cmp_eq_u32_e32 vcc, 1, v160
	v_lshl_add_u32 v18, v141, 2, v16
	s_nop 0
	s_and_saveexec_b64 s[10:11], s[6:7]
	s_cbranch_execz .Lfin_nl
	v_and_b32_e32 v142, 15, v161
	v_bfe_u32 v143, v161, 4, 2
	v_and_b32_e32 v144, 0xffffffe0, v140
	v_add_u32_e32 v144, v144, v143
	s_lshl_b32 s56, s12, 11
	s_and_b32 s56, s56, 0x2000
	v_add_u32_e32 v144, s56, v144
	v_lshlrev_b32_e32 v144, 10, v144
	s_lshl_b32 s56, s95, 8
	s_and_b32 s56, s56, 0x300
	v_add_u32_e32 v144, s56, v144
	v_lshl_add_u32 v144, v142, 4, v144
	v_mov_b32_e32 v147, v144
	v_lshlrev_b32_e32 v145, 5, v142
	global_load_dwordx4 v[100:103], v145, s[30:31]
	global_load_dwordx4 v[104:107], v145, s[30:31] offset:16
	global_load_dwordx4 v[228:231], v144, s[44:45]
	v_add_u32_e32 v144, 0x1000, v144
	global_load_dwordx4 v[232:235], v144, s[44:45]
	v_add_u32_e32 v144, 0x1000, v144
	global_load_dwordx4 v[236:239], v144, s[44:45]
	v_add_u32_e32 v144, 0x1000, v144
	global_load_dwordx4 v[240:243], v144, s[44:45]
	v_add_u32_e32 v144, 0x1000, v144
	global_load_dwordx4 v[84:87], v144, s[44:45]
	v_add_u32_e32 v144, 0x1000, v144
	global_load_dwordx4 v[88:91], v144, s[44:45]
	v_add_u32_e32 v144, 0x1000, v144
	global_load_dwordx4 v[92:95], v144, s[44:45]
	v_add_u32_e32 v144, 0x1000, v144
	global_load_dwordx4 v[96:99], v144, s[44:45]
